# LRU bwd y stores write-through (sc1) so the seam-3 release has less dirty L2 to flush
# speedup vs baseline: 1.0068x; 1.0004x over previous
; #define LAS __attribute__((address_space(3)))
; template <int dir>
; __device__ __forceinline__ void lru_pass(LAS unsigned char* lds, const Params& P, int b, int h, int q, bool dry) {
;     ...
;         } else if (!dry) {
; #pragma unroll
;             for (int i = 0; i < 2; ++i) { const int id = tid + i * NTHREADS; *(u32x4*)(Z + ZSLAB(8 + h, (size_t)b * SEQ + t0_prev + (id >> 2)) + q * 32 + (id & 3) * 8) = *(const LAS u32x4*)(TOUT + (id >> 2) * IO_NP + (id & 3) * 16); }
;         }
; __global__ void __launch_bounds__(NTHREADS, 2) fwd_megakernel(Params P) {
;     ...
;         for (int s2 = bx; s2 < 256; s2 += G) { lru_strip(lds, P, ((s2 & 7) << 5) | (s2 >> 3), false); __syncthreads(); }
.LBB0_277:
	s_ashr_i32 s1, s29, 31
	s_add_u32 s0, s26, s29
	s_waitcnt lgkmcnt(0)
	s_barrier
	s_addc_u32 s1, s27, s1
	v_add_u32_e32 v0, v158, v164
	ds_read_b128 v[0:3], v0
	v_lshl_add_u64 v[4:5], s[0:1], 0, v[140:141]
	v_lshlrev_b64 v[4:5], 8, v[4:5]
	v_lshl_add_u64 v[8:9], v[136:137], 0, v[4:5]
	v_add_u32_e32 v4, v158, v152
	ds_read_b128 v[4:7], v4
	s_waitcnt lgkmcnt(1)
	global_store_dwordx4 v[8:9], v[0:3], off sc1
	s_add_i32 s2, s2, s34
	s_cmpk_lt_i32 s2, 0x100
	v_lshl_add_u64 v[0:1], s[0:1], 0, v[138:139]
	v_lshlrev_b64 v[0:1], 8, v[0:1]
	v_lshl_add_u64 v[0:1], v[136:137], 0, v[0:1]
	v_mov_b32_e32 v200, 0x3ecc95a3
	v_mov_b32_e32 v201, 0x7f800000
	v_mov_b32_e32 v202, 0x7fc00000
	v_mov_b32_e32 v203, v156
	s_waitcnt lgkmcnt(0)
	global_store_dwordx4 v[0:1], v[4:7], off sc1
	s_barrier
	s_barrier
	s_cbranch_scc0 .LBB0_317

; #define LAS __attribute__((address_space(3)))
; template <int dir>
; __device__ __forceinline__ void lru_pass(LAS unsigned char* lds, const Params& P, int b, int h, int q, bool dry) {
;     ...
;                 } else if (!dry) {
; #pragma unroll
;                     for (int i = 0; i < 2; ++i) { const int id = tid + i * NTHREADS; *(u32x4*)(Z + ZSLAB(8 + h, (size_t)b * SEQ + t0_prev + (id >> 2)) + q * 32 + (id & 3) * 8) = *(const LAS u32x4*)(TOUT + (id >> 2) * IO_NP + (id & 3) * 16); }
.LBB0_309:
	s_waitcnt lgkmcnt(0)
	s_barrier
	s_cmp_lt_u32 s46, 2
	s_cbranch_scc1 .LBB0_311
	s_ashr_i32 s7, s78, 31
	s_add_u32 s6, s26, s78
	s_addc_u32 s7, s27, s7
	v_add_u32_e32 v32, v158, v164
	ds_read_b128 v[32:35], v32
	v_lshl_add_u64 v[36:37], s[6:7], 0, v[140:141]
	v_lshlrev_b64 v[36:37], 8, v[36:37]
	v_lshl_add_u64 v[40:41], v[136:137], 0, v[36:37]
	v_add_u32_e32 v36, v158, v152
	ds_read_b128 v[36:39], v36
	s_waitcnt lgkmcnt(1)
	global_store_dwordx4 v[40:41], v[32:35], off sc1
	s_nop 1
	v_lshl_add_u64 v[32:33], s[6:7], 0, v[138:139]
	v_lshlrev_b64 v[32:33], 8, v[32:33]
	v_lshl_add_u64 v[32:33], v[136:137], 0, v[32:33]
	s_waitcnt lgkmcnt(0)
	global_store_dwordx4 v[32:33], v[36:39], off sc1
